# baseline (speedup 1.0000x reference)
; __device__ __forceinline__ void phase_g3(PP p, const int g_wid, int wrow0, int nN, u16* P, int ldp) {
;     ...
;     EPI_TID;
;     const float* rsl = RS_LDS(par);
;     u16* Pt = P + (long)pm * 256 * ldp + pn * 256;
;     const unsigned tok0 = wc * 32 + fr;
; #pragma unroll
;     for (int bj = 0; bj < 2; ++bj)
; #pragma unroll
;       for (int n = 0; n < 2; ++n) {
;         const unsigned tok = tok0 + bj * 128 + n * 16;
;         const float rs = rsl[tok];
;         u16* pp = Pt + tok * (unsigned)ldp + wr * 64 + SWAP_FOFF(fq);
; #pragma unroll
;         for (int ai = 0; ai < 2; ++ai)
; #pragma unroll
;           for (int mp = 0; mp < 4; mp += 2) {
;             const unsigned l0 = pack2(acc[ai][bj][mp][n][0] * rs, acc[ai][bj][mp][n][1] * rs), h0 = pack2(acc[ai][bj][mp][n][2] * rs, acc[ai][bj][mp][n][3] * rs);
;             const unsigned l1 = pack2(acc[ai][bj][mp + 1][n][0] * rs, acc[ai][bj][mp + 1][n][1] * rs), h1 = pack2(acc[ai][bj][mp + 1][n][2] * rs, acc[ai][bj][mp + 1][n][3] * rs);
;             *reinterpret_cast<uint4*>(pp + ai * 128 + mp * 16) = swap_pair(l0, h0, l1, h1);
;           }
.LBB0_309:
	s_or_b64 exec, exec, s[16:17]
	s_mov_b32 s11, -1
	s_movk_i32 s13, 0x60
	v_mbcnt_lo_u32_b32 v0, s11, 0
	v_mbcnt_hi_u32_b32 v0, s11, v0
	v_readlane_b32 s11, v254, 63
	s_nop 1
	v_or_b32_e32 v0, s11, v0
	s_lshl_b32 s11, s28, 10
	v_and_b32_e32 v130, 15, v0
	v_lshrrev_b32_e32 v131, 1, v0
	s_add_i32 s11, s11, 0
	v_and_or_b32 v134, v131, s13, v130
	v_ashrrev_i32_e32 v130, 2, v0
	v_and_b32_e32 v133, 16, v0
	v_lshrrev_b32_e32 v0, 2, v0
	v_lshl_add_u32 v132, v134, 2, s11
	s_mul_hi_i32 s13, s12, s37
	s_mul_i32 s12, s12, s37
	v_and_b32_e32 v0, 12, v0
	s_lshl_b64 s[12:13], s[12:13], 1
	v_cmp_eq_u32_e32 vcc, 0, v133
	v_add_u32_e32 v133, 12, v0
	v_add_u32_e32 v135, 0x20000, v132
	s_add_u32 s11, s8, s12
	v_cndmask_b32_e32 v0, v133, v0, vcc
	ds_read2_b32 v[132:133], v135 offset1:16
	s_addc_u32 s16, s9, s13
	s_ashr_i32 s15, s14, 31
	s_lshl_b64 s[12:13], s[14:15], 1
	s_add_u32 s12, s11, s12
	v_and_b32_e32 v130, 0xffffffc0, v130
	s_addc_u32 s13, s16, s13
	v_ashrrev_i32_e32 v131, 31, v130
	v_lshl_add_u64 v[130:131], v[130:131], 1, s[12:13]
	v_lshlrev_b32_e32 v0, 1, v0
	s_waitcnt lgkmcnt(0)
	v_pk_mul_f32 v[102:103], v[102:103], v[132:133] op_sel_hi:[1,0]
	v_pk_mul_f32 v[104:105], v[104:105], v[132:133] op_sel_hi:[1,0]
	v_pk_mul_f32 v[98:99], v[98:99], v[132:133] op_sel_hi:[1,0]
	v_lshl_add_u64 v[130:131], v[130:131], 0, v[0:1]
	v_mul_u32_u24_e32 v0, s30, v134
	v_cvt_pk_bf16_f32 v102, v102, v103
	v_cvt_pk_bf16_f32 v103, v104, v105
	v_cvt_pk_bf16_f32 v104, v98, v99
	v_pk_mul_f32 v[98:99], v[100:101], v[132:133] op_sel_hi:[1,0]
	v_lshlrev_b32_e32 v0, 1, v0
	v_cvt_pk_bf16_f32 v105, v98, v99
	v_lshl_add_u64 v[130:131], v[130:131], 0, v[0:1]
	v_permlane16_swap_b32_e32 v102, v104
	v_permlane16_swap_b32_e32 v103, v105
	v_pk_mul_f32 v[98:99], v[126:127], v[132:133] op_sel_hi:[1,0]
	v_pk_mul_f32 v[100:101], v[128:129], v[132:133] op_sel_hi:[1,0]
	global_store_dwordx4 v[130:131], v[102:105], off offset:64
	v_cvt_pk_bf16_f32 v98, v98, v99
	v_cvt_pk_bf16_f32 v99, v100, v101
	v_pk_mul_f32 v[100:101], v[122:123], v[132:133] op_sel_hi:[1,0]
	v_pk_mul_f32 v[102:103], v[124:125], v[132:133] op_sel_hi:[1,0]
	v_cvt_pk_bf16_f32 v100, v100, v101
	v_cvt_pk_bf16_f32 v101, v102, v103
	s_nop 0
	v_permlane16_swap_b32_e32 v98, v100
	v_permlane16_swap_b32_e32 v99, v101
	global_store_dwordx4 v[130:131], v[98:101], off offset:256
	v_mov_b32_e32 v0, v133
	v_pk_mul_f32 v[102:103], v[108:109], v[132:133] op_sel_hi:[1,0]
	v_pk_mul_f32 v[98:99], v[110:111], v[132:133] op_sel_hi:[1,0]
	v_pk_mul_f32 v[100:101], v[112:113], v[132:133] op_sel_hi:[1,0]
	v_cvt_pk_bf16_f32 v98, v98, v99
	v_cvt_pk_bf16_f32 v99, v100, v101
	v_pk_mul_f32 v[100:101], v[106:107], v[132:133] op_sel_hi:[1,0]
	v_pk_mul_f32 v[70:71], v[70:71], v[0:1] op_sel_hi:[1,0]
	v_pk_mul_f32 v[72:73], v[72:73], v[0:1] op_sel_hi:[1,0]
	v_pk_mul_f32 v[66:67], v[66:67], v[0:1] op_sel_hi:[1,0]
	v_cvt_pk_bf16_f32 v100, v100, v101
	v_cvt_pk_bf16_f32 v101, v102, v103
	v_cvt_pk_bf16_f32 v70, v70, v71
	v_cvt_pk_bf16_f32 v71, v72, v73
	v_cvt_pk_bf16_f32 v72, v66, v67
	v_pk_mul_f32 v[66:67], v[68:69], v[0:1] op_sel_hi:[1,0]
	v_permlane16_swap_b32_e32 v98, v100
	v_permlane16_swap_b32_e32 v99, v101
	v_cvt_pk_bf16_f32 v73, v66, v67
	global_store_dwordx4 v[130:131], v[98:101], off offset:320
	v_permlane16_swap_b32_e32 v70, v72
	s_nop 0
	v_lshl_add_u64 v[98:99], v[130:131], 0, s[54:55]
	v_permlane16_swap_b32_e32 v71, v73
	v_pk_mul_f32 v[66:67], v[94:95], v[0:1] op_sel_hi:[1,0]
	v_pk_mul_f32 v[68:69], v[96:97], v[0:1] op_sel_hi:[1,0]
	global_store_dwordx4 v[98:99], v[70:73], off offset:64
	v_cvt_pk_bf16_f32 v66, v66, v67
	v_cvt_pk_bf16_f32 v67, v68, v69
	v_pk_mul_f32 v[68:69], v[90:91], v[0:1] op_sel_hi:[1,0]
	v_pk_mul_f32 v[70:71], v[92:93], v[0:1] op_sel_hi:[1,0]
	v_cvt_pk_bf16_f32 v68, v68, v69
	v_cvt_pk_bf16_f32 v69, v70, v71
	s_nop 0
	v_permlane16_swap_b32_e32 v66, v68
	v_permlane16_swap_b32_e32 v67, v69
	global_store_dwordx4 v[98:99], v[66:69], off offset:256
	v_pk_mul_f32 v[70:71], v[76:77], v[0:1] op_sel_hi:[1,0]
	s_mov_b32 s11, s55
	v_pk_mul_f32 v[66:67], v[78:79], v[0:1] op_sel_hi:[1,0]
	v_pk_mul_f32 v[68:69], v[80:81], v[0:1] op_sel_hi:[1,0]
	v_cvt_pk_bf16_f32 v66, v66, v67
	v_cvt_pk_bf16_f32 v67, v68, v69
	v_pk_mul_f32 v[68:69], v[74:75], v[0:1] op_sel_hi:[1,0]
	v_pk_mul_f32 v[86:87], v[86:87], v[0:1] op_sel_hi:[1,0]
	v_cvt_pk_bf16_f32 v68, v68, v69
	v_cvt_pk_bf16_f32 v69, v70, v71
	s_nop 0
	v_permlane16_swap_b32_e32 v66, v68
	v_permlane16_swap_b32_e32 v67, v69
	global_store_dwordx4 v[98:99], v[66:69], off offset:320
	ds_read2_b32 v[66:67], v135 offset0:128 offset1:144
	v_pk_mul_f32 v[88:89], v[88:89], v[0:1] op_sel_hi:[1,0]
	v_lshl_add_u64 v[68:69], v[98:99], 0, s[10:11]
	v_pk_mul_f32 v[82:83], v[82:83], v[0:1] op_sel_hi:[1,0]
	v_cvt_pk_bf16_f32 v86, v86, v87
	s_waitcnt lgkmcnt(0)
; __device__ __forceinline__ void phase_g3(PP p, const int g_wid, int wrow0, int nN, u16* P, int ldp) {
;     ...
; #pragma unroll
;     for (int bj = 0; bj < 2; ++bj)
; #pragma unroll
;       for (int n = 0; n < 2; ++n) {
;         const unsigned tok = tok0 + bj * 128 + n * 16;
;         const float rs = rsl[tok];
;         u16* pp = Pt + tok * (unsigned)ldp + wr * 64 + SWAP_FOFF(fq);
; #pragma unroll
;         for (int ai = 0; ai < 2; ++ai)
; #pragma unroll
;           for (int mp = 0; mp < 4; mp += 2) {
;             const unsigned l0 = pack2(acc[ai][bj][mp][n][0] * rs, acc[ai][bj][mp][n][1] * rs), h0 = pack2(acc[ai][bj][mp][n][2] * rs, acc[ai][bj][mp][n][3] * rs);
;             const unsigned l1 = pack2(acc[ai][bj][mp + 1][n][0] * rs, acc[ai][bj][mp + 1][n][1] * rs), h1 = pack2(acc[ai][bj][mp + 1][n][2] * rs, acc[ai][bj][mp + 1][n][3] * rs);
;             *reinterpret_cast<uint4*>(pp + ai * 128 + mp * 16) = swap_pair(l0, h0, l1, h1);
;           }
;       }
	v_pk_mul_f32 v[42:43], v[42:43], v[66:67] op_sel_hi:[1,0]
	v_pk_mul_f32 v[44:45], v[44:45], v[66:67] op_sel_hi:[1,0]
	v_pk_mul_f32 v[34:35], v[34:35], v[66:67] op_sel_hi:[1,0]
	v_cvt_pk_bf16_f32 v42, v42, v43
	v_cvt_pk_bf16_f32 v43, v44, v45
	v_cvt_pk_bf16_f32 v44, v34, v35
	v_pk_mul_f32 v[34:35], v[36:37], v[66:67] op_sel_hi:[1,0]
	s_nop 0
	v_permlane16_swap_b32_e32 v42, v44
	v_cvt_pk_bf16_f32 v45, v34, v35
	s_nop 1
	v_permlane16_swap_b32_e32 v43, v45
	v_pk_mul_f32 v[34:35], v[62:63], v[66:67] op_sel_hi:[1,0]
	v_pk_mul_f32 v[36:37], v[64:65], v[66:67] op_sel_hi:[1,0]
	global_store_dwordx4 v[68:69], v[42:45], off offset:64
	v_cvt_pk_bf16_f32 v34, v34, v35
	v_cvt_pk_bf16_f32 v35, v36, v37
	v_pk_mul_f32 v[36:37], v[54:55], v[66:67] op_sel_hi:[1,0]
	v_pk_mul_f32 v[42:43], v[56:57], v[66:67] op_sel_hi:[1,0]
	v_cvt_pk_bf16_f32 v36, v36, v37
	v_cvt_pk_bf16_f32 v37, v42, v43
	s_nop 0
	v_permlane16_swap_b32_e32 v34, v36
	v_permlane16_swap_b32_e32 v35, v37
	v_cvt_pk_bf16_f32 v87, v88, v89
	v_cvt_pk_bf16_f32 v88, v82, v83
	v_pk_mul_f32 v[82:83], v[84:85], v[0:1] op_sel_hi:[1,0]
	global_store_dwordx4 v[68:69], v[34:37], off offset:256
	v_mov_b32_e32 v0, v67
	v_pk_mul_f32 v[10:11], v[10:11], v[0:1] op_sel_hi:[1,0]
	v_pk_mul_f32 v[34:35], v[46:47], v[66:67] op_sel_hi:[1,0]
	v_pk_mul_f32 v[36:37], v[48:49], v[66:67] op_sel_hi:[1,0]
	v_cvt_pk_bf16_f32 v34, v34, v35
	v_cvt_pk_bf16_f32 v35, v36, v37
	v_pk_mul_f32 v[36:37], v[38:39], v[66:67] op_sel_hi:[1,0]
	v_pk_mul_f32 v[38:39], v[40:41], v[66:67] op_sel_hi:[1,0]
	v_pk_mul_f32 v[12:13], v[12:13], v[0:1] op_sel_hi:[1,0]
	v_pk_mul_f32 v[2:3], v[2:3], v[0:1] op_sel_hi:[1,0]
	v_cvt_pk_bf16_f32 v36, v36, v37
	v_cvt_pk_bf16_f32 v37, v38, v39
	v_cvt_pk_bf16_f32 v10, v10, v11
	v_cvt_pk_bf16_f32 v11, v12, v13
	v_cvt_pk_bf16_f32 v12, v2, v3
	v_pk_mul_f32 v[2:3], v[4:5], v[0:1] op_sel_hi:[1,0]
	v_permlane16_swap_b32_e32 v34, v36
	v_permlane16_swap_b32_e32 v35, v37
	v_cvt_pk_bf16_f32 v13, v2, v3
	global_store_dwordx4 v[68:69], v[34:37], off offset:320
	v_permlane16_swap_b32_e32 v10, v12
	s_nop 0
	v_lshl_add_u64 v[34:35], v[68:69], 0, s[54:55]
	v_permlane16_swap_b32_e32 v11, v13
	v_pk_mul_f32 v[2:3], v[30:31], v[0:1] op_sel_hi:[1,0]
	v_pk_mul_f32 v[4:5], v[32:33], v[0:1] op_sel_hi:[1,0]
	global_store_dwordx4 v[34:35], v[10:13], off offset:64
	v_cvt_pk_bf16_f32 v2, v2, v3
	v_cvt_pk_bf16_f32 v3, v4, v5
	v_pk_mul_f32 v[4:5], v[22:23], v[0:1] op_sel_hi:[1,0]
	v_pk_mul_f32 v[10:11], v[24:25], v[0:1] op_sel_hi:[1,0]
	v_cvt_pk_bf16_f32 v4, v4, v5
	v_cvt_pk_bf16_f32 v5, v10, v11
	s_nop 0
	v_permlane16_swap_b32_e32 v2, v4
	v_permlane16_swap_b32_e32 v3, v5
	v_pk_mul_f32 v[118:119], v[118:119], v[132:133] op_sel_hi:[1,0]
	v_pk_mul_f32 v[120:121], v[120:121], v[132:133] op_sel_hi:[1,0]
	v_pk_mul_f32 v[114:115], v[114:115], v[132:133] op_sel_hi:[1,0]
	v_pk_mul_f32 v[58:59], v[58:59], v[66:67] op_sel_hi:[1,0]
	v_pk_mul_f32 v[60:61], v[60:61], v[66:67] op_sel_hi:[1,0]
	v_pk_mul_f32 v[50:51], v[50:51], v[66:67] op_sel_hi:[1,0]
	v_pk_mul_f32 v[26:27], v[26:27], v[0:1] op_sel_hi:[1,0]
	v_pk_mul_f32 v[28:29], v[28:29], v[0:1] op_sel_hi:[1,0]
	v_pk_mul_f32 v[18:19], v[18:19], v[0:1] op_sel_hi:[1,0]
	global_store_dwordx4 v[34:35], v[2:5], off offset:256
	v_cvt_pk_bf16_f32 v118, v118, v119
	v_cvt_pk_bf16_f32 v119, v120, v121
	v_pk_mul_f32 v[2:3], v[14:15], v[0:1] op_sel_hi:[1,0]
	v_pk_mul_f32 v[4:5], v[16:17], v[0:1] op_sel_hi:[1,0]
	v_cvt_pk_bf16_f32 v120, v114, v115
	v_pk_mul_f32 v[114:115], v[116:117], v[132:133] op_sel_hi:[1,0]
	v_cvt_pk_bf16_f32 v58, v58, v59
	v_cvt_pk_bf16_f32 v59, v60, v61
	v_cvt_pk_bf16_f32 v60, v50, v51
	v_pk_mul_f32 v[50:51], v[52:53], v[66:67] op_sel_hi:[1,0]
	v_cvt_pk_bf16_f32 v26, v26, v27
	v_cvt_pk_bf16_f32 v27, v28, v29
	v_cvt_pk_bf16_f32 v28, v18, v19
	v_pk_mul_f32 v[18:19], v[20:21], v[0:1] op_sel_hi:[1,0]
	v_cvt_pk_bf16_f32 v2, v2, v3
	v_cvt_pk_bf16_f32 v3, v4, v5
	v_pk_mul_f32 v[4:5], v[6:7], v[0:1] op_sel_hi:[1,0]
	v_pk_mul_f32 v[6:7], v[8:9], v[0:1] op_sel_hi:[1,0]
	v_readlane_b32 s11, v254, 4
	v_cvt_pk_bf16_f32 v121, v114, v115
	v_cvt_pk_bf16_f32 v89, v82, v83
	v_cvt_pk_bf16_f32 v61, v50, v51
	v_cvt_pk_bf16_f32 v29, v18, v19
	v_cvt_pk_bf16_f32 v4, v4, v5
	v_cvt_pk_bf16_f32 v5, v6, v7
	s_add_i32 s26, s26, s11
	s_xor_b32 s28, s28, 1
	v_permlane16_swap_b32_e32 v118, v120
	v_permlane16_swap_b32_e32 v119, v121
	v_permlane16_swap_b32_e32 v86, v88
	v_permlane16_swap_b32_e32 v87, v89
	v_permlane16_swap_b32_e32 v58, v60
	v_permlane16_swap_b32_e32 v59, v61
	v_permlane16_swap_b32_e32 v26, v28
	v_permlane16_swap_b32_e32 v27, v29
	v_permlane16_swap_b32_e32 v2, v4
	v_permlane16_swap_b32_e32 v3, v5
	s_cmp_ge_i32 s26, s27
	global_store_dwordx4 v[130:131], v[118:121], off
	global_store_dwordx4 v[98:99], v[86:89], off
	global_store_dwordx4 v[68:69], v[58:61], off
	global_store_dwordx4 v[34:35], v[26:29], off
	global_store_dwordx4 v[34:35], v[2:5], off offset:320
	s_cbranch_scc1 .LBB0_322
